# retention step: cross-term and masked-score K/state fragment LDS reads batched ahead of their MFMAs
# speedup vs baseline: 1.0578x; 1.0116x over previous
; #define LAS __attribute__((address_space(3)))
; __device__ __forceinline__ unsigned cvtpk(float lo, float hi) { f32x2_t v = {lo, hi}; bf16x2_t b = __builtin_convertvector(v, bf16x2_t); return __builtin_bit_cast(unsigned, b); }
; __device__ __forceinline__ void ret_unit(LAS unsigned char* lds, bf16_t* U, bf16_t* OF, int b, int h, int sl, const int tid, const bool dry) {
;     ...
;       bf16x8 qf[4];
; #pragma unroll
;       for (int ks = 0; ks < 4; ++ks) qf[ks] = *(const LAS bf16x8*)(Qs + n * RT_STR + ks * 32 + quad * 8);
;       f32x4 o[4];
; #pragma unroll
;       for (int eb = 0; eb < 4; ++eb) { f32x4 a = (f32x4){0.f, 0.f, 0.f, 0.f};
; #pragma unroll
;         for (int ks = 0; ks < 4; ++ks) { const bf16x8 af = *(const LAS bf16x8*)(St + (16 * eb + c16) * RT_STR + ks * 32 + quad * 8); a = mfma16(af, qf[ks], a); }
;         o[eb] = a * dq; }
;       const float pre = dir ? gC : g1, post = dir ? 1.f : g127;
; #pragma unroll
;       for (int eb = 0; eb < 4; ++eb) st[eb] = st[eb] * pre;
; #pragma unroll 4
;       for (int s2 = 0; s2 < 4; ++s2) {
;         const LAS bf16_t* vb = Vs + (32 * s2 + 4 * quad + tq) * RT_VSTR + 4 * tp;
;         bf16x8 vf[4];
; #pragma unroll
;         for (int eb = 0; eb < 4; ++eb) { const u32x2 lo = tr_rd(vb + 16 * eb), hi = tr_rd(vb + 16 * RT_VSTR + 16 * eb); const u32x4 vv = (u32x4){lo.x, lo.y, hi.x, hi.y}; vf[eb] = __builtin_bit_cast(bf16x8, vv); }
;         const bool needed = dir ? (2 * s2 + 1 >= wid) : (2 * s2 <= wid);
;         if (needed) {
;           float pw[8];
; #pragma unroll
;           for (int hf = 0; hf < 2; ++hf) { const int mb = 2 * s2 + hf; f32x4 a = (f32x4){0.f, 0.f, 0.f, 0.f};
; #pragma unroll
;             for (int ks = 0; ks < 4; ++ks) { const bf16x8 kf = *(const LAS bf16x8*)(Ks + (16 * mb + c16) * RT_STR + ks * 32 + quad * 8); a = mfma16(kf, qf[ks], a); }
; #pragma unroll
;             for (int r = 0; r < 4; ++r) { const int m = 16 * mb + 4 * quad + r; const bool keep = dir ? (m > n) : (n >= m); pw[4 * hf + r] = keep ? a[r] * cn : 0.f; } }
;           u32x4 w; w.x = cvtpk(pw[0], pw[1]); w.y = cvtpk(pw[2], pw[3]); w.z = cvtpk(pw[4], pw[5]); w.w = cvtpk(pw[6], pw[7]);
;           const bf16x8 pf = __builtin_bit_cast(bf16x8, w);
; #pragma unroll
;           for (int eb = 0; eb < 4; ++eb) o[eb] = mfma16(vf[eb], pf, o[eb]);
.LBB0_256:
	ds_read_b128 v[54:57], v202
	ds_read_b128 v[50:53], v202 offset:64
	ds_read_b128 v[46:49], v202 offset:128
	ds_read_b128 v[42:45], v202 offset:192
	ds_read_b128 v[74:77], v203
	ds_read_b128 v[78:81], v203 offset:64
	ds_read_b128 v[82:85], v203 offset:128
	ds_read_b128 v[86:89], v203 offset:192
	ds_read_b128 v[212:215], v203 offset:4352
	ds_read_b128 v[216:219], v203 offset:4416
	ds_read_b128 v[240:243], v203 offset:4480
	ds_read_b128 v[244:247], v203 offset:4544
	s_waitcnt lgkmcnt(7)
	v_mfma_f32_16x16x32_bf16 v[58:61], v[74:77], v[54:57], 0
	s_waitcnt lgkmcnt(6)
	v_mfma_f32_16x16x32_bf16 v[58:61], v[78:81], v[50:53], v[58:61]
	s_waitcnt lgkmcnt(5)
	v_mfma_f32_16x16x32_bf16 v[58:61], v[82:85], v[46:49], v[58:61]
	s_waitcnt lgkmcnt(4)
	v_mfma_f32_16x16x32_bf16 v[58:61], v[86:89], v[42:45], v[58:61]
	ds_read_b128 v[74:77], v203 offset:8704
	ds_read_b128 v[78:81], v203 offset:8768
	ds_read_b128 v[82:85], v203 offset:8832
	ds_read_b128 v[86:89], v203 offset:8896
	s_waitcnt lgkmcnt(7)
	v_mfma_f32_16x16x32_bf16 v[62:65], v[212:215], v[54:57], 0
	s_waitcnt lgkmcnt(6)
	v_mfma_f32_16x16x32_bf16 v[62:65], v[216:219], v[50:53], v[62:65]
	s_waitcnt lgkmcnt(5)
	v_mfma_f32_16x16x32_bf16 v[62:65], v[240:243], v[46:49], v[62:65]
	s_waitcnt lgkmcnt(4)
	v_mfma_f32_16x16x32_bf16 v[62:65], v[244:247], v[42:45], v[62:65]
	ds_read_b128 v[212:215], v203 offset:13056
	ds_read_b128 v[216:219], v203 offset:13120
	ds_read_b128 v[240:243], v203 offset:13184
	ds_read_b128 v[244:247], v203 offset:13248
	s_waitcnt lgkmcnt(7)
	v_mfma_f32_16x16x32_bf16 v[66:69], v[74:77], v[54:57], 0
	s_waitcnt lgkmcnt(6)
	v_mfma_f32_16x16x32_bf16 v[66:69], v[78:81], v[50:53], v[66:69]
	s_waitcnt lgkmcnt(5)
	v_mfma_f32_16x16x32_bf16 v[66:69], v[82:85], v[46:49], v[66:69]
	s_waitcnt lgkmcnt(4)
	v_mfma_f32_16x16x32_bf16 v[66:69], v[86:89], v[42:45], v[66:69]
	s_waitcnt lgkmcnt(3)
	v_mfma_f32_16x16x32_bf16 v[70:73], v[212:215], v[54:57], 0
	s_waitcnt lgkmcnt(2)
	v_mfma_f32_16x16x32_bf16 v[70:73], v[216:219], v[50:53], v[70:73]
	s_waitcnt lgkmcnt(1)
	v_mfma_f32_16x16x32_bf16 v[70:73], v[240:243], v[46:49], v[70:73]
	s_waitcnt lgkmcnt(0)
	v_mfma_f32_16x16x32_bf16 v[90:93], v[244:247], v[42:45], v[70:73]
	ds_read_b64_tr_b16 v[82:83], v204
	ds_read_b64_tr_b16 v[74:75], v204 offset:32
	ds_read_b64_tr_b16 v[84:85], v204 offset:2304
	ds_read_b64_tr_b16 v[76:77], v204 offset:2336
	ds_read_b64_tr_b16 v[78:79], v204 offset:64
	ds_read_b64_tr_b16 v[80:81], v204 offset:2368
	ds_read_b64_tr_b16 v[86:87], v204 offset:96
	ds_read_b64_tr_b16 v[88:89], v204 offset:2400
	s_and_saveexec_b64 s[88:89], s[12:13]
	s_xor_b64 s[88:89], exec, s[88:89]
	s_or_saveexec_b64 vcc, s[88:89]
	v_pk_mul_f32 v[60:61], v[164:165], v[60:61]
	v_pk_mul_f32 v[58:59], v[154:155], v[58:59]
	v_pk_mul_f32 v[64:65], v[164:165], v[64:65]
	v_pk_mul_f32 v[62:63], v[154:155], v[62:63]
	v_pk_mul_f32 v[72:73], v[164:165], v[68:69]
	v_pk_mul_f32 v[70:71], v[154:155], v[66:67]
	v_pk_mul_f32 v[68:69], v[164:165], v[92:93]
	v_pk_mul_f32 v[66:67], v[154:155], v[90:91]
	s_xor_b64 exec, exec, vcc
	s_cbranch_execz .LBB0_258
	ds_read_b128 v[212:215], v205 offset:34816
	ds_read_b128 v[216:219], v205 offset:34880
	ds_read_b128 v[240:243], v205 offset:34944
	ds_read_b128 v[244:247], v205 offset:35008
	ds_read_b128 v[208:211], v205 offset:39168
	s_waitcnt lgkmcnt(4)
	v_mfma_f32_16x16x32_bf16 v[90:93], v[212:215], v[54:57], 0
	ds_read_b128 v[212:215], v205 offset:39232
	s_waitcnt lgkmcnt(4)
	v_mfma_f32_16x16x32_bf16 v[90:93], v[216:219], v[50:53], v[90:93]
	ds_read_b128 v[216:219], v205 offset:39296
	s_waitcnt lgkmcnt(4)
	v_mfma_f32_16x16x32_bf16 v[90:93], v[240:243], v[46:49], v[90:93]
	ds_read_b128 v[240:243], v205 offset:39360
	s_waitcnt lgkmcnt(4)
	v_mfma_f32_16x16x32_bf16 v[90:93], v[244:247], v[42:45], v[90:93]
	s_waitcnt lgkmcnt(3)
	v_mfma_f32_16x16x32_bf16 v[182:185], v[208:211], v[54:57], 0
	s_waitcnt lgkmcnt(2)
	v_mfma_f32_16x16x32_bf16 v[182:185], v[212:215], v[50:53], v[182:185]
	s_waitcnt lgkmcnt(1)
	v_mfma_f32_16x16x32_bf16 v[182:185], v[216:219], v[46:49], v[182:185]
	s_waitcnt lgkmcnt(0)
	v_mfma_f32_16x16x32_bf16 v[182:185], v[240:243], v[42:45], v[182:185]
	v_mul_f32_e32 v90, v207, v90
	v_mul_f32_e32 v91, v207, v91
	v_mul_f32_e32 v92, v207, v92
	v_mul_f32_e32 v93, v207, v93
	v_cndmask_b32_e64 v90, 0, v90, s[20:21]
	v_cndmask_b32_e64 v91, 0, v91, s[22:23]
	v_cndmask_b32_e64 v92, 0, v92, s[24:25]
	v_cndmask_b32_e64 v93, 0, v93, s[26:27]
	s_nop 1
	v_mul_f32_e32 v182, v207, v182
	v_mul_f32_e32 v183, v207, v183
	v_mul_f32_e32 v184, v207, v184
	v_mul_f32_e32 v185, v207, v185
	v_cndmask_b32_e64 v182, 0, v182, s[28:29]
	v_cndmask_b32_e64 v183, 0, v183, s[30:31]
	v_cndmask_b32_e64 v184, 0, v184, s[34:35]
	v_cndmask_b32_e64 v185, 0, v185, s[36:37]
	v_cvt_pk_bf16_f32 v90, v90, v91
	v_cvt_pk_bf16_f32 v91, v92, v93
	v_cvt_pk_bf16_f32 v92, v182, v183
	v_cvt_pk_bf16_f32 v93, v184, v185
	s_nop 1
	v_mfma_f32_16x16x32_bf16 v[58:61], v[82:85], v[90:93], v[58:61]
	v_mfma_f32_16x16x32_bf16 v[62:65], v[74:77], v[90:93], v[62:65]
	v_mfma_f32_16x16x32_bf16 v[70:73], v[78:81], v[90:93], v[70:73]
	v_mfma_f32_16x16x32_bf16 v[66:69], v[86:89], v[90:93], v[66:69]
; #define LAS __attribute__((address_space(3)))
; __device__ __forceinline__ unsigned cvtpk(float lo, float hi) { f32x2_t v = {lo, hi}; bf16x2_t b = __builtin_convertvector(v, bf16x2_t); return __builtin_bit_cast(unsigned, b); }
; __device__ __forceinline__ f32x4 mfma16(bf16x8 a, bf16x8 b, f32x4 c) { return __builtin_amdgcn_mfma_f32_16x16x32_bf16(a, b, c, 0, 0, 0); }
; __device__ __forceinline__ u32x2 tr_rd(const LAS bf16_t* p) { return __builtin_bit_cast(u32x2, __builtin_amdgcn_ds_read_tr16_b64_v4i16((LAS v4i16_t*)p)); }
; __device__ __forceinline__ void ret_unit(LAS unsigned char* lds, bf16_t* U, bf16_t* OF, int b, int h, int sl, const int tid, const bool dry) {
;     ...
;       for (int s2 = 0; s2 < 4; ++s2) {
;         const LAS bf16_t* vb = Vs + (32 * s2 + 4 * quad + tq) * RT_VSTR + 4 * tp;
;         bf16x8 vf[4];
; #pragma unroll
;         for (int eb = 0; eb < 4; ++eb) { const u32x2 lo = tr_rd(vb + 16 * eb), hi = tr_rd(vb + 16 * RT_VSTR + 16 * eb); const u32x4 vv = (u32x4){lo.x, lo.y, hi.x, hi.y}; vf[eb] = __builtin_bit_cast(bf16x8, vv); }
;         const bool needed = dir ? (2 * s2 + 1 >= wid) : (2 * s2 <= wid);
;         if (needed) {
;           float pw[8];
; #pragma unroll
;           for (int hf = 0; hf < 2; ++hf) { const int mb = 2 * s2 + hf; f32x4 a = (f32x4){0.f, 0.f, 0.f, 0.f};
; #pragma unroll
;             for (int ks = 0; ks < 4; ++ks) { const bf16x8 kf = *(const LAS bf16x8*)(Ks + (16 * mb + c16) * RT_STR + ks * 32 + quad * 8); a = mfma16(kf, qf[ks], a); }
; #pragma unroll
;             for (int r = 0; r < 4; ++r) { const int m = 16 * mb + 4 * quad + r; const bool keep = dir ? (m > n) : (n >= m); pw[4 * hf + r] = keep ? a[r] * cn : 0.f; } }
;           u32x4 w; w.x = cvtpk(pw[0], pw[1]); w.y = cvtpk(pw[2], pw[3]); w.z = cvtpk(pw[4], pw[5]); w.w = cvtpk(pw[6], pw[7]);
;           const bf16x8 pf = __builtin_bit_cast(bf16x8, w);
; #pragma unroll
;           for (int eb = 0; eb < 4; ++eb) o[eb] = mfma16(vf[eb], pf, o[eb]);
;         }
;         const LAS bf16_t* kb = Ks + (32 * s2 + 4 * quad + tq) * RT_STR + 16 * wid + 4 * tp;
;         const u32x2 klo = tr_rd(kb), khi = tr_rd(kb + 16 * RT_STR);
;         const u32x4 kk = (u32x4){klo.x, klo.y, khi.x, khi.y}; const bf16x8 bk = __builtin_bit_cast(bf16x8, kk);
; #pragma unroll
;         for (int eb = 0; eb < 4; ++eb) st[eb] = mfma16(vf[eb], bk, st[eb]);
.LBB0_258:
	s_or_b64 exec, exec, vcc
	v_mov_b32_e32 v151, v150
	v_pk_mul_f32 v[92:93], v[150:151], v[96:97]
	v_pk_mul_f32 v[90:91], v[166:167], v[94:95]
	v_pk_mul_f32 v[96:97], v[150:151], v[100:101]
	v_pk_mul_f32 v[94:95], v[166:167], v[98:99]
	v_pk_mul_f32 v[100:101], v[150:151], v[104:105]
	v_pk_mul_f32 v[98:99], v[166:167], v[102:103]
	v_pk_mul_f32 v[104:105], v[150:151], v[176:177]
	v_pk_mul_f32 v[102:103], v[166:167], v[174:175]
	ds_read_b64_tr_b16 v[174:175], v206 offset:34816
	ds_read_b64_tr_b16 v[176:177], v206 offset:39168
	s_waitcnt lgkmcnt(0)
	v_mfma_f32_16x16x32_bf16 v[82:85], v[82:85], v[174:177], v[90:93]
	v_mfma_f32_16x16x32_bf16 v[74:77], v[74:77], v[174:177], v[94:97]
	v_mfma_f32_16x16x32_bf16 v[90:93], v[78:81], v[174:177], v[98:101]
	v_mfma_f32_16x16x32_bf16 v[94:97], v[86:89], v[174:177], v[102:105]
	ds_read_b64_tr_b16 v[78:79], v204 offset:4608
	ds_read_b64_tr_b16 v[86:87], v204 offset:4640
	ds_read_b64_tr_b16 v[80:81], v204 offset:6912
	ds_read_b64_tr_b16 v[88:89], v204 offset:6944
	ds_read_b64_tr_b16 v[98:99], v204 offset:4672
	ds_read_b64_tr_b16 v[100:101], v204 offset:6976
	ds_read_b64_tr_b16 v[102:103], v204 offset:4704
	ds_read_b64_tr_b16 v[104:105], v204 offset:7008
	s_and_saveexec_b64 s[88:89], s[14:15]
	s_xor_b64 s[88:89], exec, s[88:89]
	s_andn2_saveexec_b64 vcc, s[88:89]
	s_cbranch_execz .LBB0_260
	ds_read_b128 v[212:215], v205 offset:43520
	ds_read_b128 v[216:219], v205 offset:43584
	ds_read_b128 v[240:243], v205 offset:43648
	ds_read_b128 v[244:247], v205 offset:43712
	ds_read_b128 v[208:211], v205 offset:47872
	s_waitcnt lgkmcnt(4)
	v_mfma_f32_16x16x32_bf16 v[174:177], v[212:215], v[54:57], 0
	ds_read_b128 v[212:215], v205 offset:47936
	s_waitcnt lgkmcnt(4)
	v_mfma_f32_16x16x32_bf16 v[174:177], v[216:219], v[50:53], v[174:177]
	ds_read_b128 v[216:219], v205 offset:48000
	s_waitcnt lgkmcnt(4)
	v_mfma_f32_16x16x32_bf16 v[174:177], v[240:243], v[46:49], v[174:177]
	ds_read_b128 v[240:243], v205 offset:48064
	s_waitcnt lgkmcnt(4)
	v_mfma_f32_16x16x32_bf16 v[174:177], v[244:247], v[42:45], v[174:177]
	s_waitcnt lgkmcnt(3)
	v_mfma_f32_16x16x32_bf16 v[182:185], v[208:211], v[54:57], 0
	s_waitcnt lgkmcnt(2)
	v_mfma_f32_16x16x32_bf16 v[182:185], v[212:215], v[50:53], v[182:185]
	s_waitcnt lgkmcnt(1)
	v_mfma_f32_16x16x32_bf16 v[182:185], v[216:219], v[46:49], v[182:185]
	s_waitcnt lgkmcnt(0)
	v_mfma_f32_16x16x32_bf16 v[182:185], v[240:243], v[42:45], v[182:185]
	v_mul_f32_e32 v174, v207, v174
	v_mul_f32_e32 v175, v207, v175
	v_mul_f32_e32 v176, v207, v176
	v_mul_f32_e32 v177, v207, v177
	v_cndmask_b32_e64 v174, 0, v174, s[40:41]
	v_cndmask_b32_e64 v175, 0, v175, s[38:39]
	v_cndmask_b32_e64 v176, 0, v176, s[80:81]
	v_cndmask_b32_e64 v177, 0, v177, s[42:43]
	s_nop 1
	v_mul_f32_e32 v182, v207, v182
	v_mul_f32_e32 v183, v207, v183
	v_mul_f32_e32 v184, v207, v184
	v_mul_f32_e32 v185, v207, v185
	v_cndmask_b32_e64 v182, 0, v182, s[0:1]
	v_cndmask_b32_e64 v183, 0, v183, s[60:61]
	v_cndmask_b32_e64 v184, 0, v184, s[78:79]
	v_cndmask_b32_e64 v185, 0, v185, s[96:97]
	v_cvt_pk_bf16_f32 v174, v174, v175
	v_cvt_pk_bf16_f32 v175, v176, v177
	v_cvt_pk_bf16_f32 v176, v182, v183
	v_cvt_pk_bf16_f32 v177, v184, v185
	s_nop 1
	v_mfma_f32_16x16x32_bf16 v[58:61], v[78:81], v[174:177], v[58:61]
	v_mfma_f32_16x16x32_bf16 v[62:65], v[86:89], v[174:177], v[62:65]
	v_mfma_f32_16x16x32_bf16 v[70:73], v[98:101], v[174:177], v[70:73]
	v_mfma_f32_16x16x32_bf16 v[66:69], v[102:105], v[174:177], v[66:69]
; #define LAS __attribute__((address_space(3)))
; __device__ __forceinline__ unsigned cvtpk(float lo, float hi) { f32x2_t v = {lo, hi}; bf16x2_t b = __builtin_convertvector(v, bf16x2_t); return __builtin_bit_cast(unsigned, b); }
; __device__ __forceinline__ f32x4 mfma16(bf16x8 a, bf16x8 b, f32x4 c) { return __builtin_amdgcn_mfma_f32_16x16x32_bf16(a, b, c, 0, 0, 0); }
; __device__ __forceinline__ u32x2 tr_rd(const LAS bf16_t* p) { return __builtin_bit_cast(u32x2, __builtin_amdgcn_ds_read_tr16_b64_v4i16((LAS v4i16_t*)p)); }
; __device__ __forceinline__ void ret_unit(LAS unsigned char* lds, bf16_t* U, bf16_t* OF, int b, int h, int sl, const int tid, const bool dry) {
;     ...
;       for (int s2 = 0; s2 < 4; ++s2) {
;         const LAS bf16_t* vb = Vs + (32 * s2 + 4 * quad + tq) * RT_VSTR + 4 * tp;
;         bf16x8 vf[4];
; #pragma unroll
;         for (int eb = 0; eb < 4; ++eb) { const u32x2 lo = tr_rd(vb + 16 * eb), hi = tr_rd(vb + 16 * RT_VSTR + 16 * eb); const u32x4 vv = (u32x4){lo.x, lo.y, hi.x, hi.y}; vf[eb] = __builtin_bit_cast(bf16x8, vv); }
;         const bool needed = dir ? (2 * s2 + 1 >= wid) : (2 * s2 <= wid);
;         if (needed) {
;           float pw[8];
; #pragma unroll
;           for (int hf = 0; hf < 2; ++hf) { const int mb = 2 * s2 + hf; f32x4 a = (f32x4){0.f, 0.f, 0.f, 0.f};
; #pragma unroll
;             for (int ks = 0; ks < 4; ++ks) { const bf16x8 kf = *(const LAS bf16x8*)(Ks + (16 * mb + c16) * RT_STR + ks * 32 + quad * 8); a = mfma16(kf, qf[ks], a); }
; #pragma unroll
;             for (int r = 0; r < 4; ++r) { const int m = 16 * mb + 4 * quad + r; const bool keep = dir ? (m > n) : (n >= m); pw[4 * hf + r] = keep ? a[r] * cn : 0.f; } }
;           u32x4 w; w.x = cvtpk(pw[0], pw[1]); w.y = cvtpk(pw[2], pw[3]); w.z = cvtpk(pw[4], pw[5]); w.w = cvtpk(pw[6], pw[7]);
;           const bf16x8 pf = __builtin_bit_cast(bf16x8, w);
; #pragma unroll
;           for (int eb = 0; eb < 4; ++eb) o[eb] = mfma16(vf[eb], pf, o[eb]);
;         }
;         const LAS bf16_t* kb = Ks + (32 * s2 + 4 * quad + tq) * RT_STR + 16 * wid + 4 * tp;
;         const u32x2 klo = tr_rd(kb), khi = tr_rd(kb + 16 * RT_STR);
;         const u32x4 kk = (u32x4){klo.x, klo.y, khi.x, khi.y}; const bf16x8 bk = __builtin_bit_cast(bf16x8, kk);
; #pragma unroll
;         for (int eb = 0; eb < 4; ++eb) st[eb] = mfma16(vf[eb], bk, st[eb]);
.LBB0_260:
	s_or_b64 exec, exec, vcc
	ds_read_b64_tr_b16 v[174:175], v206 offset:43520
	ds_read_b64_tr_b16 v[176:177], v206 offset:47872
	s_waitcnt lgkmcnt(0)
	v_mfma_f32_16x16x32_bf16 v[78:81], v[78:81], v[174:177], v[82:85]
	v_mfma_f32_16x16x32_bf16 v[74:77], v[86:89], v[174:177], v[74:77]
	v_mfma_f32_16x16x32_bf16 v[86:89], v[98:101], v[174:177], v[90:93]
	v_mfma_f32_16x16x32_bf16 v[90:93], v[102:105], v[174:177], v[94:97]
	ds_read_b64_tr_b16 v[82:83], v204 offset:9216
	s_nop 1
	ds_read_b64_tr_b16 v[94:95], v204 offset:9248
	ds_read_b64_tr_b16 v[84:85], v204 offset:11520
	ds_read_b64_tr_b16 v[96:97], v204 offset:11552
	ds_read_b64_tr_b16 v[98:99], v204 offset:9280
	ds_read_b64_tr_b16 v[100:101], v204 offset:11584
	ds_read_b64_tr_b16 v[102:103], v204 offset:9312
	ds_read_b64_tr_b16 v[104:105], v204 offset:11616
	s_and_saveexec_b64 s[88:89], s[16:17]
	s_xor_b64 s[88:89], exec, s[88:89]
	s_andn2_saveexec_b64 vcc, s[88:89]
	s_cbranch_execz .LBB0_262
	ds_read_b128 v[212:215], v205 offset:52224
	ds_read_b128 v[216:219], v205 offset:52288
	ds_read_b128 v[240:243], v205 offset:52352
	ds_read_b128 v[244:247], v205 offset:52416
	ds_read_b128 v[208:211], v205 offset:56576
	s_waitcnt lgkmcnt(4)
	v_mfma_f32_16x16x32_bf16 v[174:177], v[212:215], v[54:57], 0
	ds_read_b128 v[212:215], v205 offset:56640
	s_waitcnt lgkmcnt(4)
	v_mfma_f32_16x16x32_bf16 v[174:177], v[216:219], v[50:53], v[174:177]
	ds_read_b128 v[216:219], v205 offset:56704
	s_waitcnt lgkmcnt(4)
	v_mfma_f32_16x16x32_bf16 v[174:177], v[240:243], v[46:49], v[174:177]
	ds_read_b128 v[240:243], v205 offset:56768
	s_waitcnt lgkmcnt(4)
	v_mfma_f32_16x16x32_bf16 v[174:177], v[244:247], v[42:45], v[174:177]
	s_waitcnt lgkmcnt(3)
	v_mfma_f32_16x16x32_bf16 v[182:185], v[208:211], v[54:57], 0
	s_waitcnt lgkmcnt(2)
	v_mfma_f32_16x16x32_bf16 v[182:185], v[212:215], v[50:53], v[182:185]
	s_waitcnt lgkmcnt(1)
	v_mfma_f32_16x16x32_bf16 v[182:185], v[216:219], v[46:49], v[182:185]
	s_waitcnt lgkmcnt(0)
	v_mfma_f32_16x16x32_bf16 v[182:185], v[240:243], v[42:45], v[182:185]
	v_mul_f32_e32 v174, v207, v174
	v_mul_f32_e32 v175, v207, v175
	v_mul_f32_e32 v176, v207, v176
	v_mul_f32_e32 v177, v207, v177
	v_cndmask_b32_e64 v174, 0, v174, s[44:45]
	v_cndmask_b32_e64 v175, 0, v175, s[46:47]
	v_cndmask_b32_e64 v176, 0, v176, s[48:49]
	v_cndmask_b32_e64 v177, 0, v177, s[50:51]
	s_nop 1
	v_mul_f32_e32 v182, v207, v182
	v_mul_f32_e32 v183, v207, v183
	v_mul_f32_e32 v184, v207, v184
	v_mul_f32_e32 v185, v207, v185
	v_cndmask_b32_e64 v182, 0, v182, s[52:53]
	v_cndmask_b32_e64 v183, 0, v183, s[54:55]
	v_cndmask_b32_e64 v184, 0, v184, s[56:57]
	v_cndmask_b32_e64 v185, 0, v185, s[58:59]
	v_cvt_pk_bf16_f32 v174, v174, v175
	v_cvt_pk_bf16_f32 v175, v176, v177
	v_cvt_pk_bf16_f32 v176, v182, v183
	v_cvt_pk_bf16_f32 v177, v184, v185
	s_nop 1
	v_mfma_f32_16x16x32_bf16 v[58:61], v[82:85], v[174:177], v[58:61]
	v_mfma_f32_16x16x32_bf16 v[62:65], v[94:97], v[174:177], v[62:65]
	v_mfma_f32_16x16x32_bf16 v[70:73], v[98:101], v[174:177], v[70:73]
	v_mfma_f32_16x16x32_bf16 v[66:69], v[102:105], v[174:177], v[66:69]
.LBB0_262:
	s_or_b64 exec, exec, vcc
	ds_read_b64_tr_b16 v[174:175], v206 offset:52224
	ds_read_b64_tr_b16 v[176:177], v206 offset:56576
	s_waitcnt lgkmcnt(0)
	v_mfma_f32_16x16x32_bf16 v[78:81], v[82:85], v[174:177], v[78:81]
	v_mfma_f32_16x16x32_bf16 v[82:85], v[94:97], v[174:177], v[74:77]
	v_mfma_f32_16x16x32_bf16 v[86:89], v[98:101], v[174:177], v[86:89]
	v_mfma_f32_16x16x32_bf16 v[74:77], v[102:105], v[174:177], v[90:93]
	s_nop 2
	ds_read_b64_tr_b16 v[90:91], v204 offset:13824
	ds_read_b64_tr_b16 v[94:95], v204 offset:13856
	ds_read_b64_tr_b16 v[92:93], v204 offset:16128
	ds_read_b64_tr_b16 v[96:97], v204 offset:16160
	ds_read_b64_tr_b16 v[102:103], v204 offset:13888
	ds_read_b64_tr_b16 v[104:105], v204 offset:16192
	ds_read_b64_tr_b16 v[98:99], v204 offset:13920
	ds_read_b64_tr_b16 v[100:101], v204 offset:16224
	s_and_saveexec_b64 s[88:89], s[18:19]
	s_xor_b64 s[88:89], exec, s[88:89]
	s_andn2_saveexec_b64 vcc, s[88:89]
	s_cbranch_execz .LBB0_266
	ds_read_b128 v[212:215], v205 offset:60928
	ds_read_b128 v[216:219], v205 offset:60992
	ds_read_b128 v[240:243], v205 offset:61056
	ds_read_b128 v[244:247], v205 offset:61120
	ds_read_b128 v[208:211], v205 offset:65280
	s_waitcnt lgkmcnt(4)
	v_mfma_f32_16x16x32_bf16 v[174:177], v[212:215], v[54:57], 0
	ds_read_b128 v[212:215], v205 offset:65344
	s_waitcnt lgkmcnt(4)
	v_mfma_f32_16x16x32_bf16 v[174:177], v[216:219], v[50:53], v[174:177]
	ds_read_b128 v[216:219], v205 offset:65408
	s_waitcnt lgkmcnt(4)
	v_mfma_f32_16x16x32_bf16 v[174:177], v[240:243], v[46:49], v[174:177]
	ds_read_b128 v[240:243], v205 offset:65472
	s_waitcnt lgkmcnt(4)
	v_mfma_f32_16x16x32_bf16 v[174:177], v[244:247], v[42:45], v[174:177]
	s_waitcnt lgkmcnt(3)
	v_mfma_f32_16x16x32_bf16 v[182:185], v[208:211], v[54:57], 0
	s_waitcnt lgkmcnt(2)
	v_mfma_f32_16x16x32_bf16 v[182:185], v[212:215], v[50:53], v[182:185]
	s_waitcnt lgkmcnt(1)
	v_mfma_f32_16x16x32_bf16 v[182:185], v[216:219], v[46:49], v[182:185]
	s_waitcnt lgkmcnt(0)
	v_mfma_f32_16x16x32_bf16 v[182:185], v[240:243], v[42:45], v[182:185]
	v_mul_f32_e32 v174, v207, v174
	v_mul_f32_e32 v175, v207, v175
	v_mul_f32_e32 v176, v207, v176
	v_mul_f32_e32 v177, v207, v177
	v_cndmask_b32_e64 v174, 0, v174, s[62:63]
	v_cndmask_b32_e64 v175, 0, v175, s[64:65]
	v_cndmask_b32_e64 v176, 0, v176, s[66:67]
	v_cndmask_b32_e64 v177, 0, v177, s[68:69]
	s_nop 1
	v_mul_f32_e32 v182, v207, v182
	v_mul_f32_e32 v183, v207, v183
	v_mul_f32_e32 v184, v207, v184
	v_mul_f32_e32 v185, v207, v185
	v_cndmask_b32_e64 v182, 0, v182, s[70:71]
	v_cndmask_b32_e64 v183, 0, v183, s[72:73]
	v_cndmask_b32_e64 v184, 0, v184, s[74:75]
	v_cndmask_b32_e64 v185, 0, v185, s[76:77]
	v_cvt_pk_bf16_f32 v42, v174, v175
	v_cvt_pk_bf16_f32 v43, v176, v177
	v_cvt_pk_bf16_f32 v44, v182, v183
	v_cvt_pk_bf16_f32 v45, v184, v185
	s_nop 1
	v_mfma_f32_16x16x32_bf16 v[58:61], v[90:93], v[42:45], v[58:61]
	v_mfma_f32_16x16x32_bf16 v[62:65], v[94:97], v[42:45], v[62:65]
	v_mfma_f32_16x16x32_bf16 v[70:73], v[102:105], v[42:45], v[70:73]
	v_mfma_f32_16x16x32_bf16 v[66:69], v[98:101], v[42:45], v[66:69]
